# adds attention mainloop: waves 4-7 delayed by s_sleep 4 behind each per-tile barrier (stagger of the two waves per SIMD)
# baseline (speedup 1.0000x reference)
; template <typename TQ> ...
;     ...
;   int tid_o = mk_tid(); asm volatile("" : "+v"(tid_o));
;   const int tid = tid_o, wid = tid >> 6, lane = tid & 63, r32 = lane & 31, hi = lane >> 5;
;   bf16* V_lds = (bf16*)lds; bf16* K_lds = (bf16*)(lds + NBUF * SHM_V);
;   float* ws = (float*)(lds + NBUF * SHM_V + NBUF * SHM_K) + wid * 64; float* li_l = ws; float* al_l = ws + 32;
;   float m_reg = -1e30f, l_reg = 0; f32x16 o[4] = {}; bf16x8 qr[8]; bool bounded = false;
;   const TQ* Qw = Qb + (long)(wid * QBLK + r32) * LDQ + hi * 8;
;   {
;     float x[8][8]; float ss = 0.f;
; #pragma unroll
;     for (int d0 = 0; d0 < 8; ++d0) { const u32x4 raw = *reinterpret_cast<const u32x4*>(Qw + d0 * 16);
; #pragma unroll
;       for (int q = 0; q < 4; ++q) { x[d0][2 * q] = __uint_as_float(raw[q] << 16); x[d0][2 * q + 1] = __uint_as_float(raw[q] & 0xffff0000u); } }
; __global__ void __launch_bounds__(NWAVES * 64, 2) mk_fwd(Args args) {
;     ...
;                     if (ONLY_SITE != 15 && (!rep || (PROBE_ATT & 1))) for (int i = 0;; ++i) { const int L = i * G + vcu; if (L >= 768) break;
;                         int b, hq, seq; size_t qrow; const float* ropeb;
;                         if (L < 768) { b = L / 384; const int rem = L % 384; hq = rem >> 5; qrow = (size_t)b * SB + 256 + (size_t)(rem & 31) * 256; seq = SB; ropeb = (const float*)(ws + WS_ROPE) + (size_t)(rem & 31) * 256 * 128; }
;                         else { const int jx = L - 768; b = jx / 12; hq = jx % 12; qrow = (size_t)b * SB; seq = 256; ropeb = nullptr; }
;                         const size_t kvoff = (size_t)(b * 4 + hq / 3) * SB * 128;
;                         attn::attn_dense_body<attn::bf16>((const attn::bf16*)(QB_ + qrow * 1536 + hq * 128), (const attn::bf16*)(KB_ + kvoff), (const attn::bf16*)(VB_ + kvoff), MIX_ + qrow * 2048 + 512 + hq * 128, seq, (char*)lds_raw, args.in[10], ropeb);
.LBB0_890:
	s_mul_hi_i32 s1, s0, 0x2aaaaaab
	s_lshr_b32 s3, s1, 31
	s_ashr_i32 s1, s1, 6
	s_add_i32 s3, s1, s3
	s_mul_i32 s1, s3, 0x180
	s_sub_i32 s4, s0, s1
	s_lshl_b32 s0, s4, 8
	s_and_b32 s5, s0, 0x1f00
	s_lshl_b32 s0, s5, 9
	s_add_u32 s0, s70, s0
	s_addc_u32 s1, s71, 0
	s_mul_i32 s10, s3, 0x2100
	s_mul_hi_i32 s9, s3, 0x2100
	s_add_u32 s5, s10, s5
	s_addc_u32 s9, s9, 0
	s_add_u32 s48, s5, 0x100
	s_addc_u32 s49, s9, 0
	s_ashr_i32 s5, s4, 5
	s_lshl_b32 s4, s3, 2
	s_mul_i32 s3, s5, 0x56
	s_lshr_b32 s9, s3, 8
	s_bfe_u32 s3, s3, 0x1000f
	s_add_i32 s9, s9, s3
	s_sext_i32_i8 s3, s9
	s_add_i32 s4, s4, s3
	s_mul_i32 s3, s49, 0xc00
	s_mul_hi_u32 s9, s48, 0xc00
	s_add_i32 s9, s9, s3
	s_mul_i32 s3, s48, 0xc00
	s_add_u32 s3, s77, s3
	s_addc_u32 s9, s76, s9
	s_lshl_b32 s10, s5, 7
	s_ashr_i32 s11, s10, 31
	s_lshl_b64 s[54:55], s[10:11], 1
	s_add_u32 s10, s3, s54
	s_addc_u32 s11, s9, s55
	s_mul_i32 s5, s4, 0x210000
	s_mul_hi_i32 s3, s4, 0x210000
	s_add_u32 s34, s68, s5
	s_addc_u32 s35, s69, s3
	s_add_u32 s38, s66, s5
	s_addc_u32 s39, s67, s3
	s_getreg_b32 s3, hwreg(HW_REG_HW_ID, 0, 6)
	s_lshl_b32 s3, s3, 2
	s_and_b32 s3, s3, 0xfc
	s_or_b32 s3, s3, 0x27e00
	v_mov_b32_e32 v0, s3
	ds_read_b32 v0, v0
	v_mov_b64_e32 v[2:3], s[10:11]
	v_cmp_lt_i32_e32 vcc, v190, v185
	v_mov_b32_e32 v5, v177
	s_waitcnt lgkmcnt(0)
	v_readfirstlane_b32 s3, v0
	s_mov_b32 s98, s3
	v_mbcnt_lo_u32_b32 v0, -1, 0
	v_mbcnt_hi_u32_b32 v0, -1, v0
	v_cndmask_b32_e32 v4, v184, v190, vcc
	s_nop 0
	v_lshl_add_u32 v179, s3, 6, v0
	s_movk_i32 s3, 0xc00
	v_ashrrev_i32_e32 v196, 6, v179
	v_and_b32_e32 v197, 31, v179
	v_lshlrev_b32_e32 v178, 5, v196
	v_bfe_u32 v198, v179, 5, 1
	v_or_b32_e32 v0, v178, v197
	v_mad_i64_i32 v[2:3], s[10:11], v0, s3, v[2:3]
	v_lshlrev_b32_e32 v176, 4, v198
	v_and_b32_e32 v1, 32, v179
	v_lshl_add_u64 v[2:3], v[2:3], 0, v[176:177]
	global_load_dwordx4 v[116:119], v1, s[20:21] offset:464
	global_load_dwordx4 v[44:47], v1, s[20:21] offset:336
	global_load_dwordx4 v[132:135], v[2:3], off offset:224
	global_load_dwordx4 v[136:139], v[2:3], off offset:160
	global_load_dwordx4 v[140:143], v1, s[20:21] offset:448
	global_load_dwordx4 v[56:59], v1, s[20:21] offset:320
	global_load_dwordx4 v[156:159], v[2:3], off offset:128
	global_load_dwordx4 v[160:163], v[2:3], off offset:192
	global_load_dwordx4 v[148:151], v1, s[20:21] offset:400
	global_load_dwordx4 v[64:67], v1, s[20:21] offset:272
	global_load_dwordx4 v[164:167], v1, s[20:21] offset:384
	global_load_dwordx4 v[76:79], v1, s[20:21] offset:256
	global_load_dwordx4 v[92:95], v1, s[20:21]
	global_load_dwordx4 v[88:91], v1, s[20:21] offset:16
	global_load_dwordx4 v[84:87], v1, s[20:21] offset:64
	global_load_dwordx4 v[80:83], v1, s[20:21] offset:80
	global_load_dwordx4 v[96:99], v1, s[20:21] offset:128
	global_load_dwordx4 v[100:103], v1, s[20:21] offset:144
	global_load_dwordx4 v[200:203], v1, s[20:21] offset:192
	global_load_dwordx4 v[172:175], v1, s[20:21] offset:208
	global_load_dwordx4 v[204:207], v[2:3], off offset:32
	global_load_dwordx4 v[208:211], v[2:3], off offset:96
	global_load_dwordx4 v[108:111], v[2:3], off
	global_load_dwordx4 v[104:107], v[2:3], off offset:64
	v_ashrrev_i32_e32 v1, 31, v0
	v_lshlrev_b64 v[0:1], 9, v[0:1]
	v_lshlrev_b32_e32 v182, 2, v4
	v_lshlrev_b32_e32 v4, 6, v198
	v_lshl_add_u64 v[0:1], s[0:1], 0, v[0:1]
	v_lshl_add_u64 v[12:13], v[0:1], 0, v[4:5]
	global_load_dwordx4 v[52:55], v[12:13], off offset:48
	global_load_dwordx4 v[60:63], v[12:13], off offset:32
	global_load_dwordx4 v[68:71], v[12:13], off offset:16
	global_load_dwordx4 v[72:75], v[12:13], off
	global_load_dwordx4 v[32:35], v[12:13], off offset:176
	global_load_dwordx4 v[36:39], v[12:13], off offset:160
	global_load_dwordx4 v[40:43], v[12:13], off offset:144
	global_load_dwordx4 v[48:51], v[12:13], off offset:128
	global_load_dwordx4 v[16:19], v[12:13], off offset:304
	global_load_dwordx4 v[20:23], v[12:13], off offset:288
	global_load_dwordx4 v[24:27], v[12:13], off offset:272
	global_load_dwordx4 v[28:31], v[12:13], off offset:256
	global_load_dwordx4 v[0:3], v[12:13], off offset:432
	global_load_dwordx4 v[4:7], v[12:13], off offset:416
	global_load_dwordx4 v[8:11], v[12:13], off offset:400
	s_nop 0
	global_load_dwordx4 v[12:15], v[12:13], off offset:384
	s_waitcnt vmcnt(37)
	v_lshlrev_b32_e32 v122, 16, v134
	s_waitcnt vmcnt(36)
	v_lshlrev_b32_e32 v125, 16, v137
	v_and_b32_e32 v127, 0xffff0000, v137
	s_waitcnt vmcnt(34)
	v_mov_b32_e32 v129, v58
	s_waitcnt vmcnt(25)
	v_mov_b32_e32 v223, v84
	v_mov_b32_e32 v181, v86
	v_mov_b32_e32 v113, v46
	v_mov_b32_e32 v46, v119
	s_waitcnt vmcnt(21)
	v_mov_b32_e32 v222, v200
	v_mov_b32_e32 v84, v201
	s_waitcnt vmcnt(17)
	v_lshlrev_b32_e32 v235, 16, v109
	s_waitcnt vmcnt(16)
; template <typename TQ> ...
;     ...
;     float x[8][8]; float ss = 0.f;
; #pragma unroll
;     for (int d0 = 0; d0 < 8; ++d0) { const u32x4 raw = *reinterpret_cast<const u32x4*>(Qw + d0 * 16);
; #pragma unroll
;       for (int q = 0; q < 4; ++q) { x[d0][2 * q] = __uint_as_float(raw[q] << 16); x[d0][2 * q + 1] = __uint_as_float(raw[q] & 0xffff0000u); } }
; #pragma unroll
;     for (int d0 = 0; d0 < 8; ++d0)
; #pragma unroll
;       for (int e = 0; e < 8; ++e) ss += x[d0][e] * x[d0][e];
;     ss += __shfl_xor(ss, 32);
	v_lshlrev_b32_e32 v234, 16, v105
	v_and_b32_e32 v239, 0xffff0000, v109
	v_and_b32_e32 v238, 0xffff0000, v105
	v_lshlrev_b32_e32 v109, 16, v108
	v_and_b32_e32 v105, 0xffff0000, v108
	v_lshlrev_b32_e32 v108, 16, v104
	v_and_b32_e32 v104, 0xffff0000, v104
	v_pk_mul_f32 v[242:243], v[108:109], v[108:109]
	v_pk_mul_f32 v[244:245], v[104:105], v[104:105]
	v_pk_mul_f32 v[236:237], v[234:235], v[234:235]
	v_add_f32_e32 v183, v243, v245
	v_lshlrev_b32_e32 v231, 16, v110
	v_lshlrev_b32_e32 v230, 16, v106
	v_pk_mul_f32 v[240:241], v[238:239], v[238:239]
	v_add_f32_e32 v183, v237, v183
	v_lshlrev_b32_e32 v200, 16, v107
	v_and_b32_e32 v226, 0xffff0000, v107
	v_pk_mul_f32 v[232:233], v[230:231], v[230:231]
	v_and_b32_e32 v107, 0xffff0000, v110
	v_and_b32_e32 v106, 0xffff0000, v106
	v_add_f32_e32 v183, v241, v183
	v_lshlrev_b32_e32 v201, 16, v111
	v_and_b32_e32 v227, 0xffff0000, v111
	v_pk_mul_f32 v[110:111], v[106:107], v[106:107]
	v_add_f32_e32 v183, v233, v183
	v_pk_mul_f32 v[224:225], v[200:201], v[200:201]
	v_add_f32_e32 v111, v111, v183
	v_mov_b32_e32 v180, v202
	v_mov_b32_e32 v86, v203
	v_lshlrev_b32_e32 v203, 16, v204
	v_lshlrev_b32_e32 v202, 16, v208
	v_pk_mul_f32 v[228:229], v[226:227], v[226:227]
	v_add_f32_e32 v111, v225, v111
	v_mov_b32_e32 v115, v44
	v_mov_b32_e32 v44, v117
	v_lshlrev_b32_e32 v119, 16, v139
	v_and_b32_e32 v117, 0xffff0000, v139
	v_lshlrev_b32_e32 v137, 16, v159
	v_and_b32_e32 v139, 0xffff0000, v159
	v_mov_b32_e32 v159, v76
	v_mov_b32_e32 v76, v165
	v_mov_b32_e32 v165, v82
	v_mov_b32_e32 v82, v175
	v_mov_b32_e32 v171, v80
	v_mov_b32_e32 v80, v173
	v_lshlrev_b32_e32 v173, 16, v205
	v_and_b32_e32 v175, 0xffff0000, v205
	v_pk_mul_f32 v[220:221], v[202:203], v[202:203]
	v_and_b32_e32 v205, 0xffff0000, v204
	v_and_b32_e32 v204, 0xffff0000, v208
	v_add_f32_e32 v111, v229, v111
	v_mov_b32_e32 v58, v143
	v_lshlrev_b32_e32 v143, 16, v158
	v_and_b32_e32 v145, 0xffff0000, v158
	v_mov_b32_e32 v158, v164
	v_mov_b32_e32 v164, v174
	v_mov_b32_e32 v170, v172
	v_lshlrev_b32_e32 v172, 16, v209
	v_and_b32_e32 v174, 0xffff0000, v209
	v_pk_mul_f32 v[208:209], v[204:205], v[204:205]
	v_add_f32_e32 v111, v221, v111
	v_mov_b32_e32 v112, v118
	v_mov_b32_e32 v114, v116
	v_lshlrev_b32_e32 v118, 16, v135
	v_and_b32_e32 v116, 0xffff0000, v135
	v_mov_b32_e32 v128, v142
	v_mov_b32_e32 v135, v56
	v_mov_b32_e32 v56, v141
	v_mov_b32_e32 v141, v66
	v_mov_b32_e32 v66, v151
	v_lshlrev_b32_e32 v142, 16, v162
	v_mov_b32_e32 v147, v64
	v_and_b32_e32 v144, 0xffff0000, v162
	v_mov_b32_e32 v64, v149
	v_lshlrev_b32_e32 v149, 16, v157
	v_mov_b32_e32 v152, v166
	v_and_b32_e32 v151, 0xffff0000, v157
	v_lshlrev_b32_e32 v155, 16, v156
	v_lshlrev_b32_e32 v154, 16, v160
	v_and_b32_e32 v157, 0xffff0000, v156
	v_and_b32_e32 v156, 0xffff0000, v160
	v_lshlrev_b32_e32 v160, 16, v211
	v_and_b32_e32 v162, 0xffff0000, v211
	v_lshlrev_b32_e32 v166, 16, v210
	v_and_b32_e32 v168, 0xffff0000, v210
	v_pk_mul_f32 v[210:211], v[172:173], v[172:173]
	v_add_f32_e32 v111, v209, v111
	v_mov_b32_e32 v153, v78
	v_mov_b32_e32 v78, v167
	v_lshlrev_b32_e32 v167, 16, v206
	v_pk_mul_f32 v[218:219], v[174:175], v[174:175]
	v_add_f32_e32 v111, v211, v111
	v_pk_mul_f32 v[216:217], v[166:167], v[166:167]
	v_and_b32_e32 v169, 0xffff0000, v206
	v_add_f32_e32 v111, v219, v111
	v_lshlrev_b32_e32 v123, 16, v138
	v_and_b32_e32 v121, 0xffff0000, v138
	v_and_b32_e32 v120, 0xffff0000, v134
	v_lshlrev_b32_e32 v124, 16, v133
	v_and_b32_e32 v126, 0xffff0000, v133
	v_lshlrev_b32_e32 v131, 16, v136
	v_mov_b32_e32 v134, v140
	v_and_b32_e32 v133, 0xffff0000, v136
	v_lshlrev_b32_e32 v136, 16, v163
	v_mov_b32_e32 v140, v150
	v_and_b32_e32 v138, 0xffff0000, v163
	v_mov_b32_e32 v146, v148
	v_lshlrev_b32_e32 v148, 16, v161
	v_and_b32_e32 v150, 0xffff0000, v161
	v_lshlrev_b32_e32 v161, 16, v207
	v_and_b32_e32 v163, 0xffff0000, v207
	v_pk_mul_f32 v[206:207], v[168:169], v[168:169]
	v_add_f32_e32 v111, v217, v111
	v_pk_mul_f32 v[212:213], v[160:161], v[160:161]
	v_add_f32_e32 v111, v207, v111
	v_pk_mul_f32 v[214:215], v[162:163], v[162:163]
	v_add_f32_e32 v111, v213, v111
	v_add_f32_e32 v111, v215, v111
	v_add_f32_e32 v111, v242, v111
	v_add_f32_e32 v111, v244, v111
	v_add_f32_e32 v111, v236, v111
	v_add_f32_e32 v111, v240, v111
	v_add_f32_e32 v111, v232, v111
	v_add_f32_e32 v183, v110, v111
	v_add_f32_e32 v183, v224, v183
	v_add_f32_e32 v183, v228, v183
	v_add_f32_e32 v183, v220, v183
	v_add_f32_e32 v183, v208, v183
	v_add_f32_e32 v183, v210, v183
	v_add_f32_e32 v183, v218, v183
	v_add_f32_e32 v183, v216, v183
	v_add_f32_e32 v183, v206, v183
	v_mov_b32_e32 v206, v102
	v_add_f32_e32 v102, v212, v183
	v_pk_mul_f32 v[218:219], v[154:155], v[154:155]
	v_add_f32_e32 v102, v214, v102
	v_pk_mul_f32 v[216:217], v[156:157], v[156:157]
	v_add_f32_e32 v102, v219, v102
	v_pk_mul_f32 v[208:209], v[148:149], v[148:149]
	v_add_f32_e32 v102, v217, v102
	v_pk_mul_f32 v[210:211], v[150:151], v[150:151]
	v_add_f32_e32 v102, v209, v102
	v_pk_mul_f32 v[228:229], v[142:143], v[142:143]
	v_add_f32_e32 v102, v211, v102
	v_pk_mul_f32 v[220:221], v[144:145], v[144:145]
	v_add_f32_e32 v102, v229, v102
	v_pk_mul_f32 v[110:111], v[136:137], v[136:137]
	v_add_f32_e32 v102, v221, v102
	v_lshlrev_b32_e32 v130, 16, v132
	v_pk_mul_f32 v[224:225], v[138:139], v[138:139]
	v_add_f32_e32 v102, v111, v102
	v_and_b32_e32 v132, 0xffff0000, v132
	v_pk_mul_f32 v[240:241], v[130:131], v[130:131]
	v_add_f32_e32 v102, v225, v102
	v_pk_mul_f32 v[232:233], v[132:133], v[132:133]
	v_add_f32_e32 v102, v241, v102
	v_add_f32_e32 v102, v233, v102
	v_fmac_f32_e32 v102, v125, v125
	v_fmac_f32_e32 v102, v127, v127
	v_fmac_f32_e32 v102, v123, v123
	v_fmac_f32_e32 v102, v121, v121
	v_fmac_f32_e32 v102, v119, v119
	v_fmac_f32_e32 v102, v117, v117
	v_add_f32_e32 v102, v218, v102
	v_add_f32_e32 v102, v216, v102
	v_add_f32_e32 v102, v208, v102
	v_add_f32_e32 v102, v210, v102
	v_add_f32_e32 v102, v228, v102
	v_add_f32_e32 v102, v220, v102
	v_add_f32_e32 v102, v110, v102
	v_add_f32_e32 v102, v224, v102
	v_mov_b32_e32 v236, v126
	v_mov_b32_e32 v237, v124
	v_add_f32_e32 v102, v240, v102
	v_pk_mul_f32 v[236:237], v[236:237], v[236:237]
	v_add_f32_e32 v102, v232, v102
	v_mov_b32_e32 v244, v120
	v_mov_b32_e32 v245, v122
	v_add_f32_e32 v102, v237, v102
	v_pk_mul_f32 v[244:245], v[244:245], v[244:245]
	v_add_f32_e32 v102, v236, v102
	v_mov_b32_e32 v242, v116
	v_mov_b32_e32 v243, v118
	v_add_f32_e32 v102, v245, v102
	v_pk_mul_f32 v[242:243], v[242:243], v[242:243]
	v_add_f32_e32 v102, v244, v102
	v_add_f32_e32 v102, v243, v102
	v_add_f32_e32 v110, v242, v102
	ds_bpermute_b32 v111, v182, v110
	v_mov_b32_e32 v207, v90
	v_mov_b32_e32 v90, v103
	v_mov_b32_e32 v103, v88
	v_mov_b32_e32 v102, v100
	s_waitcnt lgkmcnt(0)
; template <typename TQ> ...
;     ...
;     const float rs = 1.f / sqrtf(ss * (1.f / 128.f) + 1e-6f);
; #pragma unroll
;     for (int d0 = 0; d0 < 8; ++d0) { const float* gp = qgain + 16 * d0 + 8 * hi; const f32x8 g = *reinterpret_cast<const f32x8*>(gp);
; #pragma unroll
;       for (int e = 0; e < 8; ++e) x[d0][e] *= rs * g[e]; }
;     if (rope_blk) {
;       const float* rp = rope_blk + (long)(wid * QBLK + r32) * 128;
; #pragma unroll
;       for (int a = 0; a < 2; ++a)
; #pragma unroll
;         for (int dd = 0; dd < 2; ++dd) { const float* cp = rp + 2 * (a * 32 + 16 * dd + 8 * hi);
; #pragma unroll
;           for (int e4 = 0; e4 < 4; ++e4) { const f32x4v cs = *reinterpret_cast<const f32x4v*>(cp + 4 * e4);
; #pragma unroll
;             for (int u = 0; u < 2; ++u) { const int e = 2 * e4 + u; const float c = cs[2 * u], sn = cs[2 * u + 1], x1 = x[4 * a + dd][e], x2 = x[4 * a + 2 + dd][e];
;               x[4 * a + dd][e] = x1 * c - x2 * sn; x[4 * a + 2 + dd][e] = x1 * sn + x2 * c; } } }
	v_add_f32_e32 v88, v110, v111
	v_fmamk_f32 v88, v88, 0x3c000000, v191
	v_mul_f32_e32 v100, 0x4f800000, v88
	v_cmp_gt_f32_e32 vcc, s7, v88
	s_nop 1
	v_cndmask_b32_e32 v110, v88, v100, vcc
	v_sqrt_f32_e32 v111, v110
	v_mov_b32_e32 v88, v101
	v_mov_b32_e32 v101, v94
	v_mov_b32_e32 v100, v98
	v_add_u32_e32 v94, -1, v111
	v_fma_f32 v98, -v94, v111, v110
	v_cmp_ge_f32_e64 s[40:41], 0, v98
	v_add_u32_e32 v98, 1, v111
	s_nop 0
	v_cndmask_b32_e64 v94, v111, v94, s[40:41]
	v_fma_f32 v111, -v98, v111, v110
	v_cmp_lt_f32_e64 s[40:41], 0, v111
	s_nop 1
	v_cndmask_b32_e64 v94, v94, v98, s[40:41]
	v_mul_f32_e32 v98, 0x37800000, v94
	v_cndmask_b32_e32 v94, v94, v98, vcc
	v_cmp_class_f32_e32 vcc, v110, v192
	v_mov_b32_e32 v98, v96
	s_nop 0
	v_cndmask_b32_e32 v110, v94, v110, vcc
	v_div_scale_f32 v111, s[0:1], v110, v110, 1.0
	v_rcp_f32_e32 v183, v111
	v_mov_b32_e32 v94, v99
	v_mov_b32_e32 v99, v92
	s_mov_b32 s0, 0x42700000
	v_fma_f32 v92, -v111, v183, 1.0
	v_fmac_f32_e32 v183, v92, v183
	v_div_scale_f32 v92, vcc, 1.0, v110, 1.0
	v_mul_f32_e32 v96, v92, v183
	v_fma_f32 v199, -v111, v96, v92
	v_fmac_f32_e32 v96, v199, v183
	v_fma_f32 v92, -v111, v96, v92
	v_div_fmas_f32 v92, v92, v183, v96
	v_div_fixup_f32 v96, v92, v110, 1.0
	v_mov_b32_e32 v92, v97
	v_pk_mul_f32 v[64:65], v[64:65], v[96:97] op_sel_hi:[1,0]
	v_pk_mul_f32 v[56:57], v[56:57], v[96:97] op_sel_hi:[1,0]
	v_pk_mul_f32 v[44:45], v[44:45], v[96:97] op_sel_hi:[1,0]
	v_pk_mul_f32 v[98:99], v[98:99], v[96:97] op_sel_hi:[1,0]
	v_pk_mul_f32 v[92:93], v[92:93], v[96:97] op_sel_hi:[1,0]
	v_pk_mul_f32 v[144:145], v[64:65], v[144:145]
	v_pk_mul_f32 v[64:65], v[140:141], v[96:97] op_sel_hi:[1,0]
	v_pk_mul_f32 v[132:133], v[56:57], v[132:133]
	v_pk_mul_f32 v[56:57], v[128:129], v[96:97] op_sel_hi:[1,0]
	v_pk_mul_f32 v[120:121], v[44:45], v[120:121]
	v_pk_mul_f32 v[44:45], v[112:113], v[96:97] op_sel_hi:[1,0]
	v_pk_mul_f32 v[98:99], v[98:99], v[108:109]
	v_pk_mul_f32 v[92:93], v[92:93], v[104:105]
	v_pk_mul_f32 v[88:89], v[88:89], v[96:97] op_sel_hi:[1,0]
	v_pk_mul_f32 v[136:137], v[64:65], v[136:137]
	v_pk_mul_f32 v[64:65], v[66:67], v[96:97] op_sel_hi:[1,0]
	v_pk_mul_f32 v[124:125], v[56:57], v[124:125]
	v_pk_mul_f32 v[56:57], v[58:59], v[96:97] op_sel_hi:[1,0]
	v_pk_mul_f32 v[112:113], v[44:45], v[118:119]
	v_pk_mul_f32 v[44:45], v[46:47], v[96:97] op_sel_hi:[1,0]
	v_pk_mul_f32 v[100:101], v[100:101], v[96:97] op_sel_hi:[1,0]
	v_pk_mul_f32 v[94:95], v[94:95], v[96:97] op_sel_hi:[1,0]
	v_pk_mul_f32 v[102:103], v[102:103], v[96:97] op_sel_hi:[1,0]
	v_pk_mul_f32 v[88:89], v[88:89], v[106:107]
	v_pk_mul_f32 v[104:105], v[206:207], v[96:97] op_sel_hi:[1,0]
	v_pk_mul_f32 v[90:91], v[90:91], v[96:97] op_sel_hi:[1,0]
	v_pk_mul_f32 v[106:107], v[222:223], v[96:97] op_sel_hi:[1,0]
	v_pk_mul_f32 v[84:85], v[84:85], v[96:97] op_sel_hi:[1,0]
	v_pk_mul_f32 v[108:109], v[180:181], v[96:97] op_sel_hi:[1,0]
	v_pk_mul_f32 v[86:87], v[86:87], v[96:97] op_sel_hi:[1,0]
	v_pk_mul_f32 v[110:111], v[170:171], v[96:97] op_sel_hi:[1,0]
	v_pk_mul_f32 v[80:81], v[80:81], v[96:97] op_sel_hi:[1,0]
	v_pk_mul_f32 v[164:165], v[164:165], v[96:97] op_sel_hi:[1,0]
	v_pk_mul_f32 v[82:83], v[82:83], v[96:97] op_sel_hi:[1,0]
	v_pk_mul_f32 v[158:159], v[158:159], v[96:97] op_sel_hi:[1,0]
	v_pk_mul_f32 v[76:77], v[76:77], v[96:97] op_sel_hi:[1,0]
	v_pk_mul_f32 v[152:153], v[152:153], v[96:97] op_sel_hi:[1,0]
	v_pk_mul_f32 v[78:79], v[78:79], v[96:97] op_sel_hi:[1,0]
	v_pk_mul_f32 v[146:147], v[146:147], v[96:97] op_sel_hi:[1,0]
	v_pk_mul_f32 v[138:139], v[64:65], v[138:139]
	v_pk_mul_f32 v[64:65], v[134:135], v[96:97] op_sel_hi:[1,0]
	v_pk_mul_f32 v[126:127], v[56:57], v[126:127]
	v_pk_mul_f32 v[56:57], v[114:115], v[96:97] op_sel_hi:[1,0]
	v_pk_mul_f32 v[96:97], v[44:45], v[116:117]
	s_waitcnt vmcnt(12)
	v_pk_mul_f32 v[44:45], v[72:73], v[98:99] op_sel:[0,1] op_sel_hi:[1,0]
	v_pk_mul_f32 v[46:47], v[74:75], v[92:93] op_sel:[0,1] op_sel_hi:[1,0]
	v_pk_mul_f32 v[100:101], v[100:101], v[234:235]
	v_pk_mul_f32 v[94:95], v[94:95], v[238:239]
	v_pk_mul_f32 v[114:115], v[56:57], v[122:123]
	v_sub_f32_e32 v56, v44, v45
	v_pk_mul_f32 v[44:45], v[72:73], v[98:99]
	v_sub_f32_e32 v58, v46, v47
	v_pk_mul_f32 v[46:47], v[74:75], v[92:93]
	v_add_f32_e32 v44, v45, v44
	v_add_f32_e32 v45, v47, v46
	v_pk_mul_f32 v[46:47], v[68:69], v[100:101] op_sel:[0,1] op_sel_hi:[1,0]
	v_pk_mul_f32 v[66:67], v[70:71], v[94:95] op_sel:[0,1] op_sel_hi:[1,0]
	v_pk_mul_f32 v[102:103], v[102:103], v[230:231]
	v_pk_mul_f32 v[130:131], v[64:65], v[130:131]
	v_sub_f32_e32 v64, v46, v47
	v_pk_mul_f32 v[46:47], v[68:69], v[100:101]
	v_sub_f32_e32 v65, v66, v67
	v_pk_mul_f32 v[66:67], v[70:71], v[94:95]
	v_add_f32_e32 v46, v47, v46
	v_add_f32_e32 v47, v67, v66
	v_pk_mul_f32 v[66:67], v[60:61], v[102:103] op_sel:[0,1] op_sel_hi:[1,0]
	v_pk_mul_f32 v[60:61], v[60:61], v[102:103]
	v_pk_mul_f32 v[104:105], v[104:105], v[200:201]
	v_add_f32_e32 v57, v61, v60
	v_pk_mul_f32 v[60:61], v[62:63], v[88:89] op_sel:[0,1] op_sel_hi:[1,0]
	v_pk_mul_f32 v[62:63], v[62:63], v[88:89]
	v_pk_mul_f32 v[90:91], v[90:91], v[226:227]
	v_add_f32_e32 v59, v63, v62
	v_pk_mul_f32 v[62:63], v[52:53], v[104:105] op_sel:[0,1] op_sel_hi:[1,0]
	v_pk_mul_f32 v[106:107], v[106:107], v[202:203]
	v_pk_mul_f32 v[84:85], v[84:85], v[204:205]
	v_sub_f32_e32 v60, v60, v61
	v_sub_f32_e32 v61, v62, v63
	v_pk_mul_f32 v[52:53], v[52:53], v[104:105]
	v_pk_mul_f32 v[62:63], v[54:55], v[90:91] op_sel:[0,1] op_sel_hi:[1,0]
	v_pk_mul_f32 v[54:55], v[54:55], v[90:91]
	v_pk_mul_f32 v[108:109], v[108:109], v[172:173]
	v_add_f32_e32 v52, v53, v52
	v_add_f32_e32 v53, v55, v54
	s_waitcnt vmcnt(8)
; template <typename TQ> ...
;     ...
;         for (int dd = 0; dd < 2; ++dd) { const float* cp = rp + 2 * (a * 32 + 16 * dd + 8 * hi);
; #pragma unroll
;           for (int e4 = 0; e4 < 4; ++e4) { const f32x4v cs = *reinterpret_cast<const f32x4v*>(cp + 4 * e4);
; #pragma unroll
;             for (int u = 0; u < 2; ++u) { const int e = 2 * e4 + u; const float c = cs[2 * u], sn = cs[2 * u + 1], x1 = x[4 * a + dd][e], x2 = x[4 * a + 2 + dd][e];
;               x[4 * a + dd][e] = x1 * c - x2 * sn; x[4 * a + 2 + dd][e] = x1 * sn + x2 * c; } } }
;     }
; #pragma unroll
;     for (int d0 = 0; d0 < 8; ++d0) { constexpr float Cq = SCALE * 1.4426950408889634f;
;       u32x4 w = {cvtpk(x[d0][0] * Cq, x[d0][1] * Cq), cvtpk(x[d0][2] * Cq, x[d0][3] * Cq), cvtpk(x[d0][4] * Cq, x[d0][5] * Cq), cvtpk(x[d0][6] * Cq, x[d0][7] * Cq)}; qr[d0] = *reinterpret_cast<bf16x8*>(&w); }
	v_pk_mul_f32 v[54:55], v[48:49], v[106:107] op_sel:[0,1] op_sel_hi:[1,0]
	v_pk_mul_f32 v[48:49], v[48:49], v[106:107]
	v_pk_mul_f32 v[68:69], v[50:51], v[84:85] op_sel:[0,1] op_sel_hi:[1,0]
	v_pk_mul_f32 v[50:51], v[50:51], v[84:85]
	v_pk_mul_f32 v[86:87], v[86:87], v[174:175]
	v_add_f32_e32 v48, v49, v48
	v_add_f32_e32 v49, v51, v50
	v_pk_mul_f32 v[50:51], v[40:41], v[108:109] op_sel:[0,1] op_sel_hi:[1,0]
	v_pk_mul_f32 v[110:111], v[110:111], v[166:167]
	v_sub_f32_e32 v62, v62, v63
	v_sub_f32_e32 v63, v50, v51
	v_pk_mul_f32 v[40:41], v[40:41], v[108:109]
	v_pk_mul_f32 v[50:51], v[42:43], v[86:87] op_sel:[0,1] op_sel_hi:[1,0]
	v_pk_mul_f32 v[42:43], v[42:43], v[86:87]
	v_pk_mul_f32 v[80:81], v[80:81], v[168:169]
	v_add_f32_e32 v40, v41, v40
	v_add_f32_e32 v41, v43, v42
	v_pk_mul_f32 v[42:43], v[36:37], v[110:111] op_sel:[0,1] op_sel_hi:[1,0]
	v_pk_mul_f32 v[160:161], v[164:165], v[160:161]
	v_sub_f32_e32 v54, v54, v55
	v_sub_f32_e32 v55, v68, v69
	v_sub_f32_e32 v68, v42, v43
	v_pk_mul_f32 v[36:37], v[36:37], v[110:111]
	v_pk_mul_f32 v[42:43], v[38:39], v[80:81] op_sel:[0,1] op_sel_hi:[1,0]
	v_pk_mul_f32 v[38:39], v[38:39], v[80:81]
	v_pk_mul_f32 v[82:83], v[82:83], v[162:163]
	v_add_f32_e32 v36, v37, v36
	v_add_f32_e32 v37, v39, v38
	v_pk_mul_f32 v[38:39], v[32:33], v[160:161] op_sel:[0,1] op_sel_hi:[1,0]
	v_pk_mul_f32 v[32:33], v[32:33], v[160:161]
	v_pk_mul_f32 v[154:155], v[158:159], v[154:155]
	v_add_f32_e32 v71, v33, v32
	v_pk_mul_f32 v[32:33], v[34:35], v[82:83] op_sel:[0,1] op_sel_hi:[1,0]
	v_pk_mul_f32 v[76:77], v[76:77], v[156:157]
	v_sub_f32_e32 v72, v32, v33
	v_pk_mul_f32 v[32:33], v[34:35], v[82:83]
	v_pk_mul_f32 v[148:149], v[152:153], v[148:149]
	v_add_f32_e32 v73, v33, v32
	s_waitcnt vmcnt(4)
	v_pk_mul_f32 v[32:33], v[28:29], v[154:155] op_sel:[0,1] op_sel_hi:[1,0]
	v_pk_mul_f32 v[28:29], v[28:29], v[154:155]
	v_sub_f32_e32 v74, v32, v33
	v_pk_mul_f32 v[32:33], v[30:31], v[76:77] op_sel:[0,1] op_sel_hi:[1,0]
	v_pk_mul_f32 v[30:31], v[30:31], v[76:77]
	v_pk_mul_f32 v[78:79], v[78:79], v[150:151]
	v_add_f32_e32 v28, v29, v28
	v_add_f32_e32 v29, v31, v30
	v_pk_mul_f32 v[30:31], v[24:25], v[148:149] op_sel:[0,1] op_sel_hi:[1,0]
	v_pk_mul_f32 v[142:143], v[146:147], v[142:143]
	v_sub_f32_e32 v76, v30, v31
	v_pk_mul_f32 v[24:25], v[24:25], v[148:149]
	v_pk_mul_f32 v[30:31], v[26:27], v[78:79] op_sel:[0,1] op_sel_hi:[1,0]
	v_pk_mul_f32 v[26:27], v[26:27], v[78:79]
	v_add_f32_e32 v24, v25, v24
	v_add_f32_e32 v25, v27, v26
	v_pk_mul_f32 v[26:27], v[20:21], v[142:143] op_sel:[0,1] op_sel_hi:[1,0]
	v_pk_mul_f32 v[20:21], v[20:21], v[142:143]
	v_sub_f32_e32 v78, v26, v27
	v_pk_mul_f32 v[26:27], v[22:23], v[144:145] op_sel:[0,1] op_sel_hi:[1,0]
	v_pk_mul_f32 v[22:23], v[22:23], v[144:145]
	v_add_f32_e32 v20, v21, v20
	v_add_f32_e32 v21, v23, v22
	v_pk_mul_f32 v[22:23], v[16:17], v[136:137] op_sel:[0,1] op_sel_hi:[1,0]
	v_pk_mul_f32 v[16:17], v[16:17], v[136:137]
	v_sub_f32_e32 v79, v22, v23
	v_add_f32_e32 v23, v17, v16
	v_pk_mul_f32 v[16:17], v[18:19], v[138:139] op_sel:[0,1] op_sel_hi:[1,0]
	v_sub_f32_e32 v66, v66, v67
	v_sub_f32_e32 v82, v16, v17
	v_pk_mul_f32 v[16:17], v[18:19], v[138:139]
	v_sub_f32_e32 v67, v50, v51
	v_add_f32_e32 v18, v17, v16
	s_waitcnt vmcnt(0)
	v_pk_mul_f32 v[16:17], v[12:13], v[130:131] op_sel:[0,1] op_sel_hi:[1,0]
	v_pk_mul_f32 v[12:13], v[12:13], v[130:131]
	v_sub_f32_e32 v69, v42, v43
	v_add_f32_e32 v19, v13, v12
	v_pk_mul_f32 v[12:13], v[14:15], v[132:133] op_sel:[0,1] op_sel_hi:[1,0]
	v_sub_f32_e32 v70, v38, v39
	v_sub_f32_e32 v84, v12, v13
	v_pk_mul_f32 v[12:13], v[14:15], v[132:133]
	v_sub_f32_e32 v75, v32, v33
	v_add_f32_e32 v22, v13, v12
	v_pk_mul_f32 v[12:13], v[8:9], v[124:125] op_sel:[0,1] op_sel_hi:[1,0]
	v_sub_f32_e32 v77, v30, v31
	v_sub_f32_e32 v85, v12, v13
	v_pk_mul_f32 v[12:13], v[10:11], v[126:127] op_sel:[0,1] op_sel_hi:[1,0]
	v_sub_f32_e32 v27, v26, v27
	v_sub_f32_e32 v86, v12, v13
	v_pk_mul_f32 v[12:13], v[4:5], v[114:115] op_sel:[0,1] op_sel_hi:[1,0]
	v_pk_mul_f32 v[8:9], v[8:9], v[124:125]
	v_sub_f32_e32 v87, v12, v13
	v_pk_mul_f32 v[12:13], v[6:7], v[120:121] op_sel:[0,1] op_sel_hi:[1,0]
	v_sub_f32_e32 v83, v16, v17
	v_sub_f32_e32 v88, v12, v13
	v_pk_mul_f32 v[12:13], v[0:1], v[112:113] op_sel:[0,1] op_sel_hi:[1,0]
	v_pk_mul_f32 v[10:11], v[10:11], v[126:127]
	v_sub_f32_e32 v89, v12, v13
	v_pk_mul_f32 v[12:13], v[0:1], v[112:113]
	v_pk_mul_f32 v[0:1], v[2:3], v[96:97] op_sel:[0,1] op_sel_hi:[1,0]
	v_pk_mul_f32 v[6:7], v[6:7], v[120:121]
	v_sub_f32_e32 v90, v0, v1
	v_mul_f32_e32 v0, 0x3e0293ee, v56
	v_mul_f32_e32 v1, 0x3e0293ee, v58
	v_cvt_pk_bf16_f32 v136, v0, v1
	v_mul_f32_e32 v0, 0x3e0293ee, v64
	v_mul_f32_e32 v1, 0x3e0293ee, v65
	v_cvt_pk_bf16_f32 v137, v0, v1
	v_mul_f32_e32 v0, 0x3e0293ee, v66
	v_mul_f32_e32 v1, 0x3e0293ee, v60
	v_cvt_pk_bf16_f32 v138, v0, v1
	v_mul_f32_e32 v0, 0x3e0293ee, v61
	v_mul_f32_e32 v1, 0x3e0293ee, v62
	v_cvt_pk_bf16_f32 v139, v0, v1
	v_mul_f32_e32 v0, 0x3e0293ee, v54
	v_mul_f32_e32 v1, 0x3e0293ee, v55
	v_cvt_pk_bf16_f32 v140, v0, v1
	v_mul_f32_e32 v0, 0x3e0293ee, v63
	v_mul_f32_e32 v1, 0x3e0293ee, v67
	v_cvt_pk_bf16_f32 v141, v0, v1
	v_mul_f32_e32 v0, 0x3e0293ee, v68
	v_mul_f32_e32 v1, 0x3e0293ee, v69
	v_cvt_pk_bf16_f32 v142, v0, v1
	v_mul_f32_e32 v0, 0x3e0293ee, v70
	v_mul_f32_e32 v1, 0x3e0293ee, v72
	v_cvt_pk_bf16_f32 v143, v0, v1
	v_mul_f32_e32 v0, 0x3e0293ee, v44
	v_mul_f32_e32 v1, 0x3e0293ee, v45
	v_cvt_pk_bf16_f32 v128, v0, v1
	v_mul_f32_e32 v0, 0x3e0293ee, v46
	v_mul_f32_e32 v1, 0x3e0293ee, v47
	v_cvt_pk_bf16_f32 v129, v0, v1
	v_mul_f32_e32 v0, 0x3e0293ee, v57
	v_mul_f32_e32 v1, 0x3e0293ee, v59
	v_cvt_pk_bf16_f32 v130, v0, v1
; __device__ __forceinline__ int v_st(int k, int c) { const int kk = (k & ~0xC) | ((k & 4) << 1) | ((k & 8) >> 1); return ((kk >> 3) * 4 + (c >> 5)) * 512 + ((kk & 7) * 32 + (c & 31)) * 2; }
; __device__ __forceinline__ int v_rd_base(int lane) { return ((lane & 3) << 3) | (((lane >> 2) & 3) << 6) | (((lane >> 4) & 1) << 5) | (((lane >> 5) & 1) << 8); }
; #define SLOAD(i, k0) do { sr_[i].vs0 = St::ld8(&Vh[(long)((k0) + sr) * LDK + sc]); sr_[i].vs1 = St::ld8(&Vh[(long)((k0) + 32 + sr) * LDK + sc]); \
;     sr_[i].ks0 = St::ld8(&Kh[(long)((k0) + sr) * LDK + sc]); sr_[i].ks1 = St::ld8(&Kh[(long)((k0) + 32 + sr) * LDK + sc]); } while (0)
; template <typename TQ> ...
;     ...
;     for (int d0 = 0; d0 < 8; ++d0) { constexpr float Cq = SCALE * 1.4426950408889634f;
;       u32x4 w = {cvtpk(x[d0][0] * Cq, x[d0][1] * Cq), cvtpk(x[d0][2] * Cq, x[d0][3] * Cq), cvtpk(x[d0][4] * Cq, x[d0][5] * Cq), cvtpk(x[d0][6] * Cq, x[d0][7] * Cq)}; qr[d0] = *reinterpret_cast<bf16x8*>(&w); }
;     float q2 = 0.f;
; #pragma unroll
;     for (int d0 = 0; d0 < 8; ++d0)
; #pragma unroll
;       for (int e = 0; e < 8; ++e) q2 += x[d0][e] * x[d0][e];
;     q2 += __shfl_xor(q2, 32);
;     float gk = fmaxf(fabsf(qgain[128 + lane]), fabsf(qgain[192 + lane]));
; #pragma unroll
;     for (int s = 1; s < 64; s <<= 1) gk = fmaxf(gk, __shfl_xor(gk, s));
;     constexpr float C = SCALE * 1.4426950408889634f;
;     const float Bp = sqrtf(q2) * 11.313708498984761f * gk * 1.02f * C;
;     bounded = __all(Bp < 60.f) != 0;
;     if (bounded) m_reg = 0.f;
;   }
;   const int sr = tid >> 4, sc = (tid & 15) * 8, vst0 = v_st(sr, sc), vst1 = v_st(32 + sr, sc);
;   const int vb0 = (int)(uintptr_t)V_lds + v_rd_base(lane);
;   struct { typename St::T vs0, vs1, ks0, ks1; } sr_[SDEPTH];
;     ...
;   f32x16 pA0, pA1, pB0, pB1; float mnA, mnB, alA, alB; bf16x8 pa0, pa1, pa2, pa3; const int NT = seq / KVBLK;
;   static_assert(SHM_V == SHM_K, "one buffer offset serves K and V");
;   constexpr int SE = 0, SO = SDEPTH - 1;
;   SLOAD(SE, 0); asm volatile("s_waitcnt vmcnt(0)" ::: "memory"); SWRITE(0, SE); __syncthreads();
	v_mul_f32_e32 v0, 0x3e0293ee, v52
	v_mul_f32_e32 v1, 0x3e0293ee, v53
	v_cvt_pk_bf16_f32 v131, v0, v1
	v_mul_f32_e32 v0, 0x3e0293ee, v48
	v_mul_f32_e32 v1, 0x3e0293ee, v49
	v_cvt_pk_bf16_f32 v132, v0, v1
	v_mul_f32_e32 v0, 0x3e0293ee, v40
	v_mul_f32_e32 v1, 0x3e0293ee, v41
	v_cvt_pk_bf16_f32 v133, v0, v1
	v_mul_f32_e32 v0, 0x3e0293ee, v36
	v_mul_f32_e32 v1, 0x3e0293ee, v37
	v_cvt_pk_bf16_f32 v134, v0, v1
	v_mul_f32_e32 v0, 0x3e0293ee, v71
	v_mul_f32_e32 v1, 0x3e0293ee, v73
	v_cvt_pk_bf16_f32 v135, v0, v1
	v_mul_f32_e32 v0, 0x3e0293ee, v74
	v_mul_f32_e32 v1, 0x3e0293ee, v75
	v_cvt_pk_bf16_f32 v124, v0, v1
	v_mul_f32_e32 v0, 0x3e0293ee, v76
	v_mul_f32_e32 v1, 0x3e0293ee, v77
	v_cvt_pk_bf16_f32 v125, v0, v1
	v_mul_f32_e32 v0, 0x3e0293ee, v78
	v_mul_f32_e32 v1, 0x3e0293ee, v27
	v_cvt_pk_bf16_f32 v126, v0, v1
	v_mul_f32_e32 v0, 0x3e0293ee, v79
	v_mul_f32_e32 v1, 0x3e0293ee, v82
	v_cvt_pk_bf16_f32 v127, v0, v1
	v_mul_f32_e32 v0, 0x3e0293ee, v83
	v_mul_f32_e32 v1, 0x3e0293ee, v84
	v_cvt_pk_bf16_f32 v116, v0, v1
	v_mul_f32_e32 v0, 0x3e0293ee, v85
	v_mul_f32_e32 v1, 0x3e0293ee, v86
	v_cvt_pk_bf16_f32 v117, v0, v1
	v_mul_f32_e32 v0, 0x3e0293ee, v87
	v_mul_f32_e32 v1, 0x3e0293ee, v88
	v_cvt_pk_bf16_f32 v118, v0, v1
	v_mul_f32_e32 v0, 0x3e0293ee, v89
	v_mul_f32_e32 v1, 0x3e0293ee, v90
	v_cvt_pk_bf16_f32 v119, v0, v1
	v_mul_f32_e32 v0, 0x3e0293ee, v28
	v_mul_f32_e32 v1, 0x3e0293ee, v29
	v_cvt_pk_bf16_f32 v120, v0, v1
	v_mul_f32_e32 v0, 0x3e0293ee, v24
	v_mul_f32_e32 v1, 0x3e0293ee, v25
	v_cvt_pk_bf16_f32 v121, v0, v1
	v_mul_f32_e32 v0, 0x3e0293ee, v20
	v_mul_f32_e32 v1, 0x3e0293ee, v21
	v_cvt_pk_bf16_f32 v122, v0, v1
	v_mul_f32_e32 v0, 0x3e0293ee, v23
	v_mul_f32_e32 v1, 0x3e0293ee, v18
	v_cvt_pk_bf16_f32 v123, v0, v1
	v_mul_f32_e32 v0, 0x3e0293ee, v19
	v_mul_f32_e32 v1, 0x3e0293ee, v22
	v_cvt_pk_bf16_f32 v112, v0, v1
	v_mov_b32_e32 v0, v11
	v_mov_b32_e32 v1, v9
	v_mov_b32_e32 v11, v8
	v_pk_add_f32 v[0:1], v[0:1], v[10:11]
	v_pk_mul_f32 v[4:5], v[4:5], v[114:115]
	v_pk_mul_f32 v[14:15], v[2:3], v[96:97]
	v_mul_f32_e32 v2, 0x3e0293ee, v1
	v_mul_f32_e32 v3, 0x3e0293ee, v0
	v_cvt_pk_bf16_f32 v113, v2, v3
	v_mov_b32_e32 v2, v7
	v_mov_b32_e32 v3, v5
	v_mov_b32_e32 v7, v4
	v_pk_add_f32 v[2:3], v[2:3], v[6:7]
	v_ashrrev_i32_e32 v32, 4, v179
	v_mul_f32_e32 v4, 0x3e0293ee, v3
	v_mul_f32_e32 v5, 0x3e0293ee, v2
	v_lshlrev_b32_e32 v91, 3, v179
	v_cvt_pk_bf16_f32 v114, v4, v5
	v_mov_b32_e32 v4, v15
	v_mov_b32_e32 v5, v13
	v_mov_b32_e32 v15, v12
	v_and_b32_e32 v26, 0x78, v91
	v_ashrrev_i32_e32 v33, 31, v32
	v_pk_add_f32 v[30:31], v[4:5], v[14:15]
	v_lshlrev_b32_e32 v180, 1, v26
	v_lshlrev_b64 v[16:17], 8, v[32:33]
	v_mul_f32_e32 v4, 0x3e0293ee, v31
	v_mul_f32_e32 v5, 0x3e0293ee, v30
	v_add_u32_e32 v34, 32, v32
	v_or_b32_e32 v12, v16, v180
	v_mov_b32_e32 v13, v17
	v_cvt_pk_bf16_f32 v115, v4, v5
	v_lshl_add_u64 v[4:5], s[38:39], 0, v[12:13]
	v_ashrrev_i32_e32 v35, 31, v34
	global_load_dwordx4 v[4:7], v[4:5], off
	v_lshlrev_b64 v[38:39], 8, v[34:35]
	v_or_b32_e32 v38, v38, v180
	v_lshl_add_u64 v[8:9], s[38:39], 0, v[38:39]
	v_lshl_add_u64 v[12:13], s[34:35], 0, v[12:13]
	global_load_dwordx4 v[8:11], v[8:9], off
	v_pk_mul_f32 v[80:81], v[30:31], v[30:31]
	global_load_dwordx4 v[12:15], v[12:13], off
	v_mul_f32_e32 v31, v56, v56
	v_fmac_f32_e32 v31, v58, v58
	v_pk_mul_f32 v[42:43], v[0:1], v[0:1]
	v_lshl_add_u64 v[0:1], s[34:35], 0, v[38:39]
	v_fmac_f32_e32 v31, v64, v64
	v_pk_mul_f32 v[50:51], v[2:3], v[2:3]
	global_load_dwordx4 v[0:3], v[0:1], off
	v_fmac_f32_e32 v31, v65, v65
	v_fmac_f32_e32 v31, v66, v66
	v_fmac_f32_e32 v31, v60, v60
	v_fmac_f32_e32 v31, v61, v61
	v_fmac_f32_e32 v31, v62, v62
	v_fmac_f32_e32 v31, v54, v54
	v_fmac_f32_e32 v31, v55, v55
	v_fmac_f32_e32 v31, v63, v63
	v_fmac_f32_e32 v31, v67, v67
	v_fmac_f32_e32 v31, v68, v68
	v_fmac_f32_e32 v31, v69, v69
	v_fmac_f32_e32 v31, v70, v70
	v_and_b32_e32 v199, 63, v179
	v_fmac_f32_e32 v31, v72, v72
	v_fmac_f32_e32 v31, v44, v44
	v_lshlrev_b32_e32 v30, 2, v199
	v_fmac_f32_e32 v31, v45, v45
	global_load_dword v44, v30, s[20:21] offset:512
	global_load_dword v45, v30, s[20:21] offset:768
	v_fmac_f32_e32 v31, v46, v46
	v_fmac_f32_e32 v31, v47, v47
	v_fmac_f32_e32 v31, v57, v57
	v_fmac_f32_e32 v31, v59, v59
	v_fmac_f32_e32 v31, v52, v52
	v_fmac_f32_e32 v31, v53, v53
	v_fmac_f32_e32 v31, v48, v48
	v_fmac_f32_e32 v31, v49, v49
	v_fmac_f32_e32 v31, v40, v40
	v_fmac_f32_e32 v31, v41, v41
	v_fmac_f32_e32 v31, v36, v36
	v_fmac_f32_e32 v31, v37, v37
	v_fmac_f32_e32 v31, v71, v71
	v_fmac_f32_e32 v31, v73, v73
	v_fmac_f32_e32 v31, v74, v74
	v_fmac_f32_e32 v31, v75, v75
	v_fmac_f32_e32 v31, v76, v76
	v_fmac_f32_e32 v31, v77, v77
	v_fmac_f32_e32 v31, v78, v78
	v_fmac_f32_e32 v31, v27, v27
	v_and_b32_e32 v27, 0xfffff0, v32
	v_lshlrev_b32_e32 v30, 1, v32
	v_and_or_b32 v27, v30, 8, v27
	v_lshrrev_b32_e32 v30, 1, v32
	v_lshrrev_b32_e32 v27, 1, v27
	v_bfe_u32 v33, v91, 5, 2
	v_and_b32_e32 v35, 3, v32
	v_or_b32_e32 v27, v27, v33
	v_and_or_b32 v30, v30, 4, v35
	v_lshlrev_b32_e32 v27, 9, v27
	v_lshlrev_b32_e32 v30, 6, v30
	v_and_b32_e32 v35, 48, v180
	v_or3_b32 v204, v27, v30, v35
	v_and_b32_e32 v27, 0xfffff0, v34
	v_lshlrev_b32_e32 v36, 1, v34
	v_and_or_b32 v27, v36, 8, v27
	v_lshrrev_b32_e32 v27, 1, v27
	v_or_b32_e32 v27, v27, v33
	v_lshlrev_b32_e32 v27, 9, v27
	v_or3_b32 v205, v27, v30, v35
	v_add_u32_e32 v27, 0, v204
	s_waitcnt vmcnt(0)
	v_add_u32_e32 v30, 0, v205
	v_fmac_f32_e32 v31, v79, v79
	v_fmac_f32_e32 v31, v82, v82
	v_fmac_f32_e32 v31, v83, v83
	v_fmac_f32_e32 v31, v84, v84
	s_waitcnt vmcnt(5)
	ds_write_b128 v27, v[4:7]
	v_lshlrev_b32_e32 v4, 8, v32
	v_and_b32_e32 v5, 0x70, v179
	v_bitop3_b32 v208, v180, v4, v5 bitop3:0xde
	v_add_u32_e32 v4, 0, v208
	s_waitcnt vmcnt(4)
	ds_write_b128 v30, v[8:11]
	v_lshlrev_b32_e32 v40, 8, v197
	s_waitcnt vmcnt(3)
	ds_write_b128 v4, v[12:15] offset:49152
	v_lshlrev_b32_e32 v4, 8, v34
	v_bitop3_b32 v210, v180, v4, v5 bitop3:0xde
	v_add_u32_e32 v4, 0, v210
	v_fmac_f32_e32 v31, v85, v85
	v_fmac_f32_e32 v31, v86, v86
	v_fmac_f32_e32 v31, v87, v87
	s_waitcnt vmcnt(2)
	ds_write_b128 v4, v[0:3] offset:49152
	v_lshlrev_b32_e32 v0, 4, v179
	v_and_b32_e32 v41, 0x70, v0
	v_bitop3_b32 v213, v176, v40, v41 bitop3:0xde
	v_add_u32_e32 v4, 0, v213
	s_waitcnt lgkmcnt(0)
	s_barrier
; __device__ __forceinline__ void qkt(f32x16& p0, f32x16& p1, const bf16* Ks, const bf16x8* qr, int r32, int hi) {
;   p0 = f32x16{}; p1 = f32x16{};
;   for (int d0 = 0; d0 < 8; ++d0) { int cb = (d0 * 16 + hi * 8) * 2;
;     bf16x8 b0 = *reinterpret_cast<const bf16x8*>((const char*)Ks + KSWZ(r32, cb));
;     bf16x8 b1 = *reinterpret_cast<const bf16x8*>((const char*)Ks + KSWZ(32 + r32, cb));
;     p0 = __builtin_amdgcn_mfma_f32_32x32x16_bf16(b0, qr[d0], p0, 0, 0, 0);
;     p1 = __builtin_amdgcn_mfma_f32_32x32x16_bf16(b1, qr[d0], p1, 0, 0, 0); }
; template <typename TQ> ...
;     ...
;     float q2 = 0.f;
; #pragma unroll
;     for (int d0 = 0; d0 < 8; ++d0)
; #pragma unroll
;       for (int e = 0; e < 8; ++e) q2 += x[d0][e] * x[d0][e];
;     q2 += __shfl_xor(q2, 32);
;     float gk = fmaxf(fabsf(qgain[128 + lane]), fabsf(qgain[192 + lane]));
; #pragma unroll
;     for (int s = 1; s < 64; s <<= 1) gk = fmaxf(gk, __shfl_xor(gk, s));
;     constexpr float C = SCALE * 1.4426950408889634f;
;     const float Bp = sqrtf(q2) * 11.313708498984761f * gk * 1.02f * C;
;     bounded = __all(Bp < 60.f) != 0;
;     if (bounded) m_reg = 0.f;
	ds_read_b128 v[0:3], v4 offset:49152
	ds_read_b128 v[32:35], v4 offset:57344
	v_fmac_f32_e32 v31, v88, v88
	v_fmac_f32_e32 v31, v89, v89
	v_fmac_f32_e32 v31, v90, v90
	v_fmac_f32_e32 v31, v28, v28
	v_fmac_f32_e32 v31, v29, v29
	v_fmac_f32_e32 v31, v24, v24
	v_or_b32_e32 v24, 32, v176
	v_bitop3_b32 v215, v24, v40, v41 bitop3:0xde
	v_add_u32_e32 v24, 0, v215
	v_fmac_f32_e32 v31, v25, v25
	ds_read_b128 v[36:39], v24 offset:49152
	s_waitcnt lgkmcnt(2)
	v_mfma_f32_32x32x16_bf16 v[0:15], v[0:3], v[136:139], 0
	v_fmac_f32_e32 v31, v20, v20
	v_fmac_f32_e32 v31, v21, v21
	s_waitcnt vmcnt(0)
	v_max_f32_e64 v20, |v45|, |v45|
	v_max_f32_e64 v21, |v44|, |v44|
	v_cmp_lt_i32_e32 vcc, v188, v185
	v_max_f32_e32 v20, v21, v20
	v_or_b32_e32 v92, 64, v176
	s_waitcnt lgkmcnt(1)
	v_mfma_f32_32x32x16_bf16 v[64:79], v[32:35], v[136:139], 0
	ds_read_b128 v[32:35], v24 offset:57344
	v_cndmask_b32_e32 v21, v184, v188, vcc
	v_lshlrev_b32_e32 v21, 2, v21
	ds_bpermute_b32 v21, v21, v20
	v_bitop3_b32 v214, v92, v40, v41 bitop3:0xde
	v_fmac_f32_e32 v31, v23, v23
	v_add_u32_e32 v23, 0, v214
	s_waitcnt lgkmcnt(2)
	v_mfma_f32_32x32x16_bf16 v[0:15], v[36:39], v[140:143], v[0:15]
	ds_read_b128 v[36:39], v23 offset:49152
	v_fmac_f32_e32 v31, v18, v18
	s_waitcnt lgkmcnt(1)
	v_max_f32_e32 v18, v21, v21
	v_fmac_f32_e32 v31, v19, v19
	v_max_f32_e32 v29, v20, v18
	ds_read_b128 v[18:21], v23 offset:57344
	v_cmp_lt_i32_e32 vcc, v189, v185
	v_mfma_f32_32x32x16_bf16 v[64:79], v[32:35], v[140:143], v[64:79]
	v_fmac_f32_e32 v31, v22, v22
	v_cndmask_b32_e32 v22, v184, v189, vcc
	v_lshlrev_b32_e32 v22, 2, v22
	v_add_f32_e32 v28, v43, v31
	ds_bpermute_b32 v31, v22, v29
	v_or_b32_e32 v22, 0x60, v176
	v_bitop3_b32 v211, v22, v40, v41 bitop3:0xde
	v_add_u32_e32 v32, 0, v211
	ds_read_b128 v[22:25], v32 offset:49152
	s_waitcnt lgkmcnt(3)
	v_mfma_f32_32x32x16_bf16 v[0:15], v[36:39], v[128:131], v[0:15]
	v_cmp_lt_i32_e32 vcc, v187, v185
	v_mov_b32_e32 v203, 1.0
	s_waitcnt lgkmcnt(2)
	v_mfma_f32_32x32x16_bf16 v[64:79], v[18:21], v[128:131], v[64:79]
	s_waitcnt lgkmcnt(1)
	v_max_f32_e32 v18, v31, v31
	v_max_f32_e32 v29, v29, v18
	v_cndmask_b32_e32 v18, v184, v187, vcc
	v_lshlrev_b32_e32 v18, 2, v18
	ds_bpermute_b32 v31, v18, v29
	ds_read_b128 v[18:21], v32 offset:57344
	v_cmp_lt_i32_e32 vcc, v186, v185
	s_waitcnt lgkmcnt(2)
	v_mfma_f32_32x32x16_bf16 v[0:15], v[22:25], v[132:135], v[0:15]
	v_add_f32_e32 v22, v42, v28
	v_add_f32_e32 v28, v51, v22
	v_or_b32_e32 v22, 0x80, v176
	v_bitop3_b32 v209, v22, v40, v41 bitop3:0xde
	v_add_u32_e32 v32, 0, v209
	ds_read_b128 v[22:25], v32 offset:49152
	s_waitcnt lgkmcnt(2)
	v_max_f32_e32 v31, v31, v31
	s_waitcnt lgkmcnt(1)
	v_mfma_f32_32x32x16_bf16 v[64:79], v[18:21], v[132:135], v[64:79]
	v_cndmask_b32_e32 v18, v184, v186, vcc
	v_max_f32_e32 v29, v29, v31
	v_lshlrev_b32_e32 v18, 2, v18
	ds_bpermute_b32 v31, v18, v29
	ds_read_b128 v[18:21], v32 offset:57344
	v_cmp_lt_i32_e32 vcc, v193, v185
	v_add_f32_e32 v28, v50, v28
	s_waitcnt lgkmcnt(2)
	v_mfma_f32_32x32x16_bf16 v[0:15], v[22:25], v[124:127], v[0:15]
	s_waitcnt lgkmcnt(1)
	v_max_f32_e32 v22, v31, v31
	v_max_f32_e32 v29, v29, v22
	v_or_b32_e32 v22, 0xa0, v176
	v_bitop3_b32 v206, v22, v40, v41 bitop3:0xde
	v_add_u32_e32 v31, 0, v206
	ds_read_b128 v[22:25], v31 offset:49152
	v_add_f32_e32 v28, v81, v28
	s_waitcnt lgkmcnt(1)
	v_mfma_f32_32x32x16_bf16 v[64:79], v[18:21], v[124:127], v[64:79]
	v_cndmask_b32_e32 v18, v184, v193, vcc
	v_lshlrev_b32_e32 v18, 2, v18
	ds_bpermute_b32 v32, v18, v29
	ds_read_b128 v[18:21], v31 offset:57344
	v_add_f32_e32 v28, v80, v28
	ds_bpermute_b32 v33, v182, v28
	s_waitcnt lgkmcnt(3)
	v_mfma_f32_32x32x16_bf16 v[0:15], v[22:25], v[116:119], v[0:15]
	s_waitcnt lgkmcnt(2)
	v_max_f32_e32 v22, v32, v32
	v_max_f32_e32 v29, v29, v22
	v_or_b32_e32 v22, 0xc0, v176
	v_bitop3_b32 v207, v22, v40, v41 bitop3:0xde
	v_add_u32_e32 v32, 0, v207
	ds_read_b128 v[22:25], v32 offset:49152
	ds_bpermute_b32 v31, v182, v29
	s_waitcnt lgkmcnt(3)
	v_mfma_f32_32x32x16_bf16 v[64:79], v[18:21], v[116:119], v[64:79]
	s_waitcnt lgkmcnt(2)
	v_add_f32_e32 v18, v28, v33
	v_mul_f32_e32 v19, 0x4f800000, v18
	v_cmp_gt_f32_e32 vcc, s7, v18
	s_waitcnt lgkmcnt(0)
	v_max_f32_e32 v31, v31, v31
	v_max_f32_e32 v29, v29, v31
	v_cndmask_b32_e32 v28, v18, v19, vcc
	v_sqrt_f32_e32 v33, v28
	ds_read_b128 v[18:21], v32 offset:57344
	v_mfma_f32_32x32x16_bf16 v[0:15], v[22:25], v[120:123], v[0:15]
	v_add_u32_e32 v22, -1, v33
	v_fma_f32 v23, -v22, v33, v28
	v_cmp_ge_f32_e64 s[40:41], 0, v23
	v_add_u32_e32 v23, 1, v33
	v_fma_f32 v24, -v23, v33, v28
	v_cndmask_b32_e64 v22, v33, v22, s[40:41]
	v_cmp_lt_f32_e64 s[40:41], 0, v24
	s_waitcnt lgkmcnt(0)
	v_mfma_f32_32x32x16_bf16 v[64:79], v[18:21], v[120:123], v[64:79]
	v_or_b32_e32 v18, 0xe0, v176
	v_cndmask_b32_e64 v22, v22, v23, s[40:41]
	v_mul_f32_e32 v23, 0x37800000, v22
	v_bitop3_b32 v212, v18, v40, v41 bitop3:0xde
	v_cndmask_b32_e32 v22, v22, v23, vcc
	v_cmp_class_f32_e32 vcc, v28, v192
	v_add_u32_e32 v25, 0, v212
	ds_read_b128 v[18:21], v25 offset:49152
	v_cndmask_b32_e32 v22, v22, v28, vcc
	v_mul_f32_e32 v28, 0x413504f3, v22
	ds_read_b128 v[22:25], v25 offset:57344
	s_waitcnt lgkmcnt(1)
	v_mfma_f32_32x32x16_bf16 v[0:15], v[18:21], v[112:115], v[0:15]
	v_mul_f32_e32 v18, v29, v28
	v_mul_f32_e32 v18, 0x3f828f5c, v18
	v_mul_f32_e32 v18, 0x3e0293ee, v18
	v_cmp_gt_f32_e32 vcc, s0, v18
	s_cmp_lg_u64 vcc, exec
	s_cselect_b64 s[0:1], -1, 0
	s_cmp_eq_u64 vcc, exec
	s_waitcnt lgkmcnt(0)
	v_mfma_f32_32x32x16_bf16 v[64:79], v[22:25], v[112:115], v[64:79]
	s_cbranch_scc1 .LBB0_892
; __device__ __forceinline__ void partialSM(f32x16& p0, f32x16& p1, float& m_reg, float& mn, float& alpha, bool bounded) {
;   constexpr float THRL = THR * 1.4426950408889634f;
;   if (bounded) { mn = m_reg; alpha = 1.f; }
;   else {
;     float pmax = p0[0]; for (int r = 1; r < 16; ++r) pmax = fmaxf(pmax, p0[r]); for (int r = 0; r < 16; ++r) pmax = fmaxf(pmax, p1[r]);
;     { auto rr = __builtin_amdgcn_permlane32_swap(__float_as_uint(pmax), __float_as_uint(pmax), false, false);
;       pmax = fmaxf(__uint_as_float(rr[0]), __uint_as_float(rr[1])); }
;     if (__builtin_expect(__all(pmax - m_reg <= THRL), 1)) { mn = m_reg; alpha = 1.f; }
;     else { mn = fmaxf(m_reg, pmax); alpha = __builtin_amdgcn_exp2f(m_reg - mn); m_reg = mn; }
;     for (int r = 0; r < 16; ++r) p0[r] -= mn; for (int r = 0; r < 16; ++r) p1[r] -= mn;
;   }
	s_nop 1
	v_max_f32_e32 v18, v1, v1
	v_max_f32_e32 v19, v0, v0
	v_max_f32_e32 v18, v19, v18
	v_max3_f32 v18, v18, v2, v3
	v_max3_f32 v18, v18, v4, v5
	v_max3_f32 v18, v18, v6, v7
	v_max3_f32 v18, v18, v8, v9
	v_max3_f32 v18, v18, v10, v11
	v_max3_f32 v18, v18, v12, v13
	v_max3_f32 v18, v18, v14, v15
	v_max3_f32 v18, v18, v64, v65
	v_max3_f32 v18, v18, v66, v67
	v_max3_f32 v18, v18, v68, v69
	v_max3_f32 v18, v18, v70, v71
	v_max3_f32 v18, v18, v72, v73
	v_max3_f32 v18, v18, v74, v75
	v_max3_f32 v18, v18, v76, v77
	v_max3_f32 v18, v18, v78, v79
	v_mov_b32_e32 v19, v18
	s_nop 1
	v_permlane32_swap_b32_e32 v18, v19
	v_max_f32_e32 v19, v19, v19
	v_max_f32_e32 v18, v18, v18
	v_max_f32_e32 v18, v18, v19
	v_add_f32_e32 v19, 0x7149f2ca, v18
	v_max_f32_e32 v18, 0xf149f2ca, v18
	v_cmp_ge_f32_e32 vcc, s8, v19
	v_sub_f32_e32 v19, 0xf149f2ca, v18
	v_exp_f32_e32 v19, v19
	s_cmp_eq_u64 vcc, exec
	s_cselect_b64 vcc, -1, 0
	v_mov_b32_e32 v20, 0xf149f2ca
	v_cndmask_b32_e32 v201, v18, v20, vcc
	v_cndmask_b32_e64 v203, v19, 1.0, vcc
	v_sub_f32_e32 v15, v15, v201
	v_sub_f32_e32 v14, v14, v201
	v_sub_f32_e32 v13, v13, v201
	v_sub_f32_e32 v12, v12, v201
	v_sub_f32_e32 v11, v11, v201
	v_sub_f32_e32 v10, v10, v201
	v_sub_f32_e32 v9, v9, v201
	v_sub_f32_e32 v8, v8, v201
	v_sub_f32_e32 v7, v7, v201
	v_sub_f32_e32 v6, v6, v201
	v_sub_f32_e32 v5, v5, v201
	v_sub_f32_e32 v4, v4, v201
	v_sub_f32_e32 v3, v3, v201
	v_sub_f32_e32 v2, v2, v201
	v_sub_f32_e32 v1, v1, v201
	v_sub_f32_e32 v0, v0, v201
	v_sub_f32_e32 v79, v79, v201
	v_sub_f32_e32 v78, v78, v201
	v_sub_f32_e32 v77, v77, v201
	v_sub_f32_e32 v76, v76, v201
	v_sub_f32_e32 v75, v75, v201
	v_sub_f32_e32 v74, v74, v201
	v_sub_f32_e32 v73, v73, v201
	v_sub_f32_e32 v72, v72, v201
	v_sub_f32_e32 v71, v71, v201
	v_sub_f32_e32 v70, v70, v201
	v_sub_f32_e32 v69, v69, v201
	v_sub_f32_e32 v68, v68, v201
	v_sub_f32_e32 v67, v67, v201
	v_sub_f32_e32 v66, v66, v201
	v_sub_f32_e32 v65, v65, v201
	v_sub_f32_e32 v64, v64, v201
	s_branch .LBB0_893

; #define SBAR() __builtin_amdgcn_sched_barrier(0)
; #define SLOAD(i, k0) do { sr_[i].vs0 = St::ld8(&Vh[(long)((k0) + sr) * LDK + sc]); sr_[i].vs1 = St::ld8(&Vh[(long)((k0) + 32 + sr) * LDK + sc]); \
;     sr_[i].ks0 = St::ld8(&Kh[(long)((k0) + sr) * LDK + sc]); sr_[i].ks1 = St::ld8(&Kh[(long)((k0) + 32 + sr) * LDK + sc]); } while (0)
; template <typename TQ> ...
;     ...
;   for (int j = 1; j + 1 < NT; j += 2) {
;     SBAR(); qkt(pB0, pB1, (bf16*)((char*)K_lds + o_cur), qr, r32, hi);
;     finishSM(pA0, pA1, alA, l_reg, pa0, pa1, pa2, pa3); SBAR();
;     SLOAD(SO, (j + SDEPTH) * KVBLK); SBAR();
.LBB0_894:
	s_cmp_lt_u32 s98, 4
	s_cbranch_scc1 .Lstg_a
	s_sleep 4

; #define SBAR() __builtin_amdgcn_sched_barrier(0)
; #define SLOAD(i, k0) do { sr_[i].vs0 = St::ld8(&Vh[(long)((k0) + sr) * LDK + sc]); sr_[i].vs1 = St::ld8(&Vh[(long)((k0) + 32 + sr) * LDK + sc]); \
;     sr_[i].ks0 = St::ld8(&Kh[(long)((k0) + sr) * LDK + sc]); sr_[i].ks1 = St::ld8(&Kh[(long)((k0) + 32 + sr) * LDK + sc]); } while (0)
; #define RESC(a) do { if (__any((a) < 1.f)) { if (hi == 0) al_l[r32] = (a); asm volatile("s_waitcnt lgkmcnt(0)" ::: "memory"); \
;     for (int d = 0; d < 4; ++d) for (int r = 0; r < 16; ++r) o[d][r] *= al_l[crow(r, hi)]; } } while (0)
; __device__ __forceinline__ void partialSM(f32x16& p0, f32x16& p1, float& m_reg, float& mn, float& alpha, bool bounded) {
;     ...
;   for (int r = 0; r < 16; ++r) p0[r] = __builtin_amdgcn_exp2f(p0[r]);
; }
; __device__ __forceinline__ void finishSM(f32x16& p0, f32x16& p1, float alpha, float& l_reg, bf16x8& pa0, bf16x8& pa1, bf16x8& pa2, bf16x8& pa3) {
;   for (int r = 0; r < 16; ++r) p1[r] = __builtin_amdgcn_exp2f(p1[r]);
;   float ps = 0; for (int r = 0; r < 16; ++r) ps += p0[r]; for (int r = 0; r < 16; ++r) ps += p1[r];
;   { auto rr = __builtin_amdgcn_permlane32_swap(__float_as_uint(ps), __float_as_uint(ps), false, false);
;     ps = __uint_as_float(rr[0]) + __uint_as_float(rr[1]); }
;   l_reg = l_reg * alpha + ps;
;     ...
;   PK4(p0, 0, pa0); PK4(p0, 8, pa1); PK4(p1, 0, pa2); PK4(p1, 8, pa3);
; template <typename TQ> ...
;     ...
;     RESC(alB); __syncthreads();
;     SBAR(); qkt(pA0, pA1, (bf16*)((char*)K_lds + o_nxt), qr, r32, hi);
;     finishSM(pB0, pB1, alB, l_reg, pa0, pa1, pa2, pa3); SBAR();
;     if (SDEPTH == 1 || j + 3 < NT) SLOAD(SE, (j + 1 + SDEPTH) * KVBLK); SBAR();
.LBB0_900:
	v_exp_f32_e32 v220, v96
	v_exp_f32_e32 v230, v97
	v_exp_f32_e32 v231, v98
	v_exp_f32_e32 v232, v99
	v_exp_f32_e32 v233, v100
	v_exp_f32_e32 v234, v101
	v_exp_f32_e32 v235, v102
	v_exp_f32_e32 v236, v103
	v_exp_f32_e32 v237, v104
	v_exp_f32_e32 v238, v105
	v_exp_f32_e32 v239, v106
	v_exp_f32_e32 v240, v107
	v_exp_f32_e32 v241, v108
	v_exp_f32_e32 v242, v109
	v_exp_f32_e32 v243, v110
	v_exp_f32_e32 v244, v111
	s_waitcnt lgkmcnt(0)
	s_barrier
	s_cmp_lt_u32 s98, 4
	s_cbranch_scc1 .Lstg_b
	s_sleep 4
.Lstg_b:
	v_add_u32_e32 v68, s12, v213
	ds_read_b128 v[64:67], v68 offset:49152
	ds_read_b128 v[68:71], v68 offset:57344
	v_add_u32_e32 v226, s12, v215
	ds_read_b128 v[222:225], v226 offset:49152
	ds_read_b128 v[226:229], v226 offset:57344
	v_exp_f32_e32 v245, v86
	s_waitcnt lgkmcnt(3)
	v_mfma_f32_32x32x16_bf16 v[96:111], v[64:67], v[136:139], 0
	v_exp_f32_e32 v246, v87
	v_exp_f32_e32 v247, v88
	v_exp_f32_e32 v248, v89
	v_exp_f32_e32 v249, v90
	v_exp_f32_e32 v250, v91
	v_exp_f32_e32 v251, v92
	v_exp_f32_e32 v252, v93
	s_waitcnt lgkmcnt(2)
	v_mfma_f32_32x32x16_bf16 v[64:79], v[68:71], v[136:139], 0
	v_exp_f32_e32 v194, v94
	v_exp_f32_e32 v95, v95
	s_waitcnt lgkmcnt(1)
	v_mfma_f32_32x32x16_bf16 v[96:111], v[222:225], v[140:143], v[96:111]
	s_waitcnt lgkmcnt(0)
	v_mfma_f32_32x32x16_bf16 v[64:79], v[226:229], v[140:143], v[64:79]
	v_add_u32_e32 v226, s12, v214
	ds_read_b128 v[222:225], v226 offset:49152
	ds_read_b128 v[226:229], v226 offset:57344
	s_waitcnt lgkmcnt(1)
	v_mfma_f32_32x32x16_bf16 v[96:111], v[222:225], v[128:131], v[96:111]
	s_waitcnt lgkmcnt(0)
	v_mfma_f32_32x32x16_bf16 v[64:79], v[226:229], v[128:131], v[64:79]
	v_add_u32_e32 v226, s12, v211
	ds_read_b128 v[222:225], v226 offset:49152
	ds_read_b128 v[226:229], v226 offset:57344
	s_waitcnt lgkmcnt(1)
	v_mfma_f32_32x32x16_bf16 v[96:111], v[222:225], v[132:135], v[96:111]
	s_waitcnt lgkmcnt(0)
	v_mfma_f32_32x32x16_bf16 v[64:79], v[226:229], v[132:135], v[64:79]
	v_add_u32_e32 v226, s12, v209
	ds_read_b128 v[222:225], v226 offset:49152
	ds_read_b128 v[226:229], v226 offset:57344
	s_waitcnt lgkmcnt(1)
	v_mfma_f32_32x32x16_bf16 v[96:111], v[222:225], v[124:127], v[96:111]
	s_waitcnt lgkmcnt(0)
	v_mfma_f32_32x32x16_bf16 v[64:79], v[226:229], v[124:127], v[64:79]
	v_add_u32_e32 v226, s12, v206
	ds_read_b128 v[222:225], v226 offset:49152
	ds_read_b128 v[226:229], v226 offset:57344
	s_waitcnt lgkmcnt(1)
	v_mfma_f32_32x32x16_bf16 v[96:111], v[222:225], v[116:119], v[96:111]
	s_waitcnt lgkmcnt(0)
	v_mfma_f32_32x32x16_bf16 v[64:79], v[226:229], v[116:119], v[64:79]
	v_add_u32_e32 v226, s12, v207
	ds_read_b128 v[222:225], v226 offset:49152
	ds_read_b128 v[226:229], v226 offset:57344
	s_waitcnt lgkmcnt(1)
	v_mfma_f32_32x32x16_bf16 v[96:111], v[222:225], v[120:123], v[96:111]
	s_waitcnt lgkmcnt(0)
	v_mfma_f32_32x32x16_bf16 v[64:79], v[226:229], v[120:123], v[64:79]
	v_add_u32_e32 v226, s12, v212
	ds_read_b128 v[222:225], v226 offset:49152
	ds_read_b128 v[226:229], v226 offset:57344
	s_waitcnt lgkmcnt(1)
	v_mfma_f32_32x32x16_bf16 v[96:111], v[222:225], v[112:115], v[96:111]
	v_exp_f32_e32 v224, v80
	v_add_f32_e32 v80, 0, v220
	v_add_f32_e32 v80, v230, v80
	v_add_f32_e32 v80, v231, v80
	v_add_f32_e32 v80, v232, v80
	v_add_f32_e32 v80, v233, v80
	v_add_f32_e32 v80, v234, v80
	v_add_f32_e32 v80, v235, v80
	v_add_f32_e32 v80, v236, v80
	v_add_f32_e32 v80, v237, v80
	v_add_f32_e32 v80, v238, v80
	v_add_f32_e32 v80, v239, v80
	v_add_f32_e32 v80, v240, v80
	v_add_f32_e32 v80, v241, v80
	v_exp_f32_e32 v225, v81
	v_add_f32_e32 v80, v242, v80
	s_waitcnt lgkmcnt(0)
	v_mfma_f32_32x32x16_bf16 v[64:79], v[226:229], v[112:115], v[64:79]
	v_exp_f32_e32 v226, v82
	v_add_f32_e32 v80, v243, v80
	v_exp_f32_e32 v227, v83
	v_add_f32_e32 v80, v244, v80
	v_exp_f32_e32 v228, v84
	v_add_f32_e32 v80, v224, v80
	v_exp_f32_e32 v229, v85
	v_add_f32_e32 v80, v225, v80
	v_add_f32_e32 v80, v226, v80
	v_add_f32_e32 v80, v227, v80
	v_add_f32_e32 v80, v228, v80
	v_add_f32_e32 v80, v229, v80
	v_add_f32_e32 v80, v245, v80
	v_add_f32_e32 v80, v246, v80
	v_add_f32_e32 v80, v247, v80
	v_add_f32_e32 v80, v248, v80
	v_add_f32_e32 v80, v249, v80
	v_add_f32_e32 v80, v250, v80
	v_add_f32_e32 v80, v251, v80
	v_add_f32_e32 v80, v252, v80
	v_add_f32_e32 v80, v194, v80
	v_add_f32_e32 v222, v95, v80
	v_mov_b32_e32 v223, v222
	v_cvt_pk_bf16_f32 v80, v220, v230
	v_cvt_pk_bf16_f32 v81, v231, v232
	v_cvt_pk_bf16_f32 v82, v233, v234
	v_cvt_pk_bf16_f32 v83, v235, v236
	v_cvt_pk_bf16_f32 v84, v237, v238
	v_cvt_pk_bf16_f32 v85, v239, v240
	v_cvt_pk_bf16_f32 v86, v241, v242
	v_cvt_pk_bf16_f32 v87, v243, v244
	v_cvt_pk_bf16_f32 v88, v224, v225
	v_cvt_pk_bf16_f32 v89, v226, v227
	v_cvt_pk_bf16_f32 v90, v228, v229
	v_cvt_pk_bf16_f32 v91, v245, v246
	v_cvt_pk_bf16_f32 v92, v247, v248
	v_cvt_pk_bf16_f32 v93, v249, v250
	v_cvt_pk_bf16_f32 v94, v251, v252
	v_cvt_pk_bf16_f32 v95, v194, v95
	s_nop 1
	v_permlane32_swap_b32_e32 v222, v223
	v_permlane32_swap_b32_e32 v80, v82
	v_permlane32_swap_b32_e32 v81, v83
	v_permlane32_swap_b32_e32 v84, v86
	v_permlane32_swap_b32_e32 v85, v87
	v_permlane32_swap_b32_e32 v88, v90
	v_permlane32_swap_b32_e32 v89, v91
	v_permlane32_swap_b32_e32 v92, v94
	v_permlane32_swap_b32_e32 v93, v95
	s_cmpk_gt_u32 s3, 0x80
	s_cselect_b64 s[34:35], -1, 0
	s_and_b64 vcc, exec, s[34:35]
	s_cbranch_vccnz .LBB0_902
	v_add_co_u32_e32 v144, vcc, 0xffffe000, v182
	s_nop 1
	v_addc_co_u32_e32 v145, vcc, -1, v183, vcc
	v_add_co_u32_e32 v148, vcc, 0xfeefe000, v182
	s_nop 1
	v_addc_co_u32_e32 v149, vcc, -1, v183, vcc
	v_add_co_u32_e32 v156, vcc, 0xfef00000, v182
	global_load_dwordx4 v[144:147], v[144:145], off
	s_nop 0
	global_load_dwordx4 v[148:151], v[148:149], off
	v_addc_co_u32_e32 v157, vcc, -1, v183, vcc
	global_load_dwordx4 v[152:155], v[182:183], off
	s_nop 0
	global_load_dwordx4 v[156:159], v[156:157], off

; #define LAS __attribute__((address_space(3)))
; __global__ void __launch_bounds__(NWAVES * 64, 2) mk_fwd(Args args) {
;     extern __shared__ __attribute__((aligned(16))) unsigned char lds_raw[];
;     LAS unsigned char* lds = (LAS unsigned char*)lds_raw;
;     const int tid = threadIdx.x, lane = 0, wave = __builtin_amdgcn_readfirstlane(tid >> 6);
	.amdhsa_kernel _Z6mk_fwd4Args
		.amdhsa_group_segment_fixed_size 0
		.amdhsa_private_segment_fixed_size 0
		.amdhsa_kernarg_size 416
		.amdhsa_user_sgpr_count 2
		.amdhsa_user_sgpr_dispatch_ptr 0
		.amdhsa_user_sgpr_queue_ptr 0
		.amdhsa_user_sgpr_kernarg_segment_ptr 1
		.amdhsa_user_sgpr_dispatch_id 0
		.amdhsa_user_sgpr_kernarg_preload_length 0
		.amdhsa_user_sgpr_kernarg_preload_offset 0
		.amdhsa_user_sgpr_private_segment_size 0
		.amdhsa_uses_dynamic_stack 0
		.amdhsa_enable_private_segment 0
		.amdhsa_system_sgpr_workgroup_id_x 1
		.amdhsa_system_sgpr_workgroup_id_y 0
		.amdhsa_system_sgpr_workgroup_id_z 0
		.amdhsa_system_sgpr_workgroup_info 0
		.amdhsa_system_vgpr_workitem_id 0
		.amdhsa_next_free_vgpr 256
		.amdhsa_next_free_sgpr 102
		.amdhsa_accum_offset 256
		.amdhsa_reserve_vcc 1
		.amdhsa_float_round_mode_32 0
		.amdhsa_float_round_mode_16_64 0
		.amdhsa_float_denorm_mode_32 3
		.amdhsa_float_denorm_mode_16_64 3
		.amdhsa_dx10_clamp 1
		.amdhsa_ieee_mode 1
		.amdhsa_fp16_overflow 0
		.amdhsa_tg_split 0
		.amdhsa_exception_fp_ieee_invalid_op 0
		.amdhsa_exception_fp_denorm_src 0
		.amdhsa_exception_fp_ieee_div_zero 0
		.amdhsa_exception_fp_ieee_overflow 0
		.amdhsa_exception_fp_ieee_underflow 0
		.amdhsa_exception_fp_ieee_inexact 0
		.amdhsa_exception_int_div_zero 0
	.end_amdhsa_kernel

; __global__ void __launch_bounds__(NWAVES * 64, 2) mk_fwd(Args args) {
;     extern __shared__ __attribute__((aligned(16))) unsigned char lds_raw[];
amdhsa.kernels:
  - .agpr_count:     0
    .args:
      - .offset:         0
        .size:           160
        .value_kind:     by_value
      - .offset:         160
        .size:           4
        .value_kind:     hidden_block_count_x
      - .offset:         164
        .size:           4
        .value_kind:     hidden_block_count_y
      - .offset:         168
        .size:           4
        .value_kind:     hidden_block_count_z
      - .offset:         172
        .size:           2
        .value_kind:     hidden_group_size_x
      - .offset:         174
        .size:           2
        .value_kind:     hidden_group_size_y
      - .offset:         176
        .size:           2
        .value_kind:     hidden_group_size_z
      - .offset:         178
        .size:           2
        .value_kind:     hidden_remainder_x
      - .offset:         180
        .size:           2
        .value_kind:     hidden_remainder_y
      - .offset:         182
        .size:           2
        .value_kind:     hidden_remainder_z
      - .offset:         200
        .size:           8
        .value_kind:     hidden_global_offset_x
      - .offset:         208
        .size:           8
        .value_kind:     hidden_global_offset_y
      - .offset:         216
        .size:           8
        .value_kind:     hidden_global_offset_z
      - .offset:         224
        .size:           2
        .value_kind:     hidden_grid_dims
      - .offset:         280
        .size:           4
        .value_kind:     hidden_dynamic_lds_size
    .group_segment_fixed_size: 0
    .kernarg_segment_align: 8
    .kernarg_segment_size: 416
    .language:       OpenCL C
    .language_version:
      - 2
      - 0
    .max_flat_workgroup_size: 512
    .name:           _Z6mk_fwd4Args
    .private_segment_fixed_size: 0
    .sgpr_count:     108
    .sgpr_spill_count: 190
    .symbol:         _Z6mk_fwd4Args.kd
    .uniform_work_group_size: 1
    .uses_dynamic_stack: false
    .vgpr_count:     256
    .vgpr_spill_count: 0
    .wavefront_size: 64
